# GEMM K-loops: three s_nop per iteration removed by placing the DMA address add between the m0 write and the LDS-DMA
# baseline (speedup 1.0000x reference)
.LBB0_169:
	s_add_u32 s42, s40, 0xfff80080
	s_addc_u32 s43, s41, -1
	s_add_i32 s52, 0, 0x10000
	s_cmp_eq_u32 s51, 28
	s_cselect_b32 s45, s13, s43
	s_cselect_b32 s44, s47, s42
	s_cselect_b32 s43, s11, s50
	s_cselect_b32 s42, s48, s49
	s_add_i32 s54, 0, 0x14000
	ds_read_b128 v[130:133], v236
	ds_read_b128 v[134:137], v236 offset:1024
	ds_read_b128 v[138:141], v236 offset:2048
	ds_read_b128 v[142:145], v236 offset:3072
	ds_read_b128 v[170:173], v237
	ds_read_b128 v[184:187], v237 offset:1024
	ds_read_b128 v[188:191], v237 offset:2048
	ds_read_b128 v[192:195], v237 offset:3072
	s_add_i32 m0, s14, 0xc000
	ds_read_b128 v[196:199], v183
	ds_read_b128 v[200:203], v183 offset:1024
	ds_read_b128 v[210:213], v183 offset:2048
	ds_read_b128 v[214:217], v183 offset:3072
	ds_read_b128 v[218:221], v183 offset:4096
	ds_read_b128 v[222:225], v183 offset:5120
	ds_read_b128 v[226:229], v183 offset:6144
	ds_read_b128 v[230:233], v183 offset:7168
	global_load_lds_dwordx4 v166, s[40:41]
	s_add_i32 m0, s14, 0xe000
	s_nop 0
	global_load_lds_dwordx4 v168, s[40:41]
	s_waitcnt vmcnt(8) lgkmcnt(0)
	s_barrier
	v_mfma_f32_16x16x32_bf16 v[126:129], v[130:133], v[196:199], v[126:129]
	v_mfma_f32_16x16x32_bf16 v[122:125], v[138:141], v[196:199], v[122:125]
	v_mfma_f32_16x16x32_bf16 v[118:121], v[130:133], v[210:213], v[118:121]
	v_mfma_f32_16x16x32_bf16 v[110:113], v[138:141], v[210:213], v[110:113]
	v_mfma_f32_16x16x32_bf16 v[102:105], v[130:133], v[218:221], v[102:105]
	v_mfma_f32_16x16x32_bf16 v[94:97], v[138:141], v[218:221], v[94:97]
	v_mfma_f32_16x16x32_bf16 v[86:89], v[130:133], v[226:229], v[86:89]
	v_mfma_f32_16x16x32_bf16 v[78:81], v[138:141], v[226:229], v[78:81]
	v_mfma_f32_16x16x32_bf16 v[126:129], v[134:137], v[200:203], v[126:129]
	v_mfma_f32_16x16x32_bf16 v[122:125], v[142:145], v[200:203], v[122:125]
	v_mfma_f32_16x16x32_bf16 v[118:121], v[134:137], v[214:217], v[118:121]
	v_mfma_f32_16x16x32_bf16 v[110:113], v[142:145], v[214:217], v[110:113]
	v_mfma_f32_16x16x32_bf16 v[102:105], v[134:137], v[222:225], v[102:105]
	v_mfma_f32_16x16x32_bf16 v[94:97], v[142:145], v[222:225], v[94:97]
	v_mfma_f32_16x16x32_bf16 v[86:89], v[134:137], v[230:233], v[86:89]
	v_mfma_f32_16x16x32_bf16 v[78:81], v[142:145], v[230:233], v[78:81]
	v_mfma_f32_16x16x32_bf16 v[114:117], v[170:173], v[196:199], v[114:117]
	v_mfma_f32_16x16x32_bf16 v[106:109], v[188:191], v[196:199], v[106:109]
	v_mfma_f32_16x16x32_bf16 v[98:101], v[170:173], v[210:213], v[98:101]
	v_mfma_f32_16x16x32_bf16 v[90:93], v[188:191], v[210:213], v[90:93]
	v_mfma_f32_16x16x32_bf16 v[82:85], v[170:173], v[218:221], v[82:85]
	v_mfma_f32_16x16x32_bf16 v[74:77], v[188:191], v[218:221], v[74:77]
	v_mfma_f32_16x16x32_bf16 v[70:73], v[170:173], v[226:229], v[70:73]
	v_mfma_f32_16x16x32_bf16 v[66:69], v[188:191], v[226:229], v[66:69]
	v_mfma_f32_16x16x32_bf16 v[114:117], v[184:187], v[200:203], v[114:117]
	v_mfma_f32_16x16x32_bf16 v[106:109], v[192:195], v[200:203], v[106:109]
	v_mfma_f32_16x16x32_bf16 v[98:101], v[184:187], v[214:217], v[98:101]
	v_mfma_f32_16x16x32_bf16 v[90:93], v[192:195], v[214:217], v[90:93]
	v_mfma_f32_16x16x32_bf16 v[82:85], v[184:187], v[222:225], v[82:85]
	v_mfma_f32_16x16x32_bf16 v[74:77], v[192:195], v[222:225], v[74:77]
	v_mfma_f32_16x16x32_bf16 v[70:73], v[184:187], v[230:233], v[70:73]
	v_mfma_f32_16x16x32_bf16 v[66:69], v[192:195], v[230:233], v[66:69]
	s_barrier
	s_add_i32 s52, s52, s5
	s_mov_b32 m0, s52
	ds_read_b128 v[196:199], v183 offset:16384
	ds_read_b128 v[200:203], v183 offset:17408
	ds_read_b128 v[210:213], v183 offset:18432
	ds_read_b128 v[214:217], v183 offset:19456
	ds_read_b128 v[218:221], v183 offset:20480
	ds_read_b128 v[222:225], v183 offset:21504
	ds_read_b128 v[226:229], v183 offset:22528
	ds_read_b128 v[230:233], v183 offset:23552
	v_lshl_add_u64 v[154:155], s[42:43], 0, v[162:163]
	global_load_lds_dwordx4 v[154:155], off
	s_add_i32 m0, s52, 0x2000
	s_add_u32 s52, s42, 0x80000
	v_lshl_add_u64 v[156:157], s[42:43], 0, v[158:159]
	s_addc_u32 s53, s43, 0
	s_add_i32 s54, s54, s5
	global_load_lds_dwordx4 v[156:157], off
	s_mov_b32 m0, s54
	v_lshl_add_u64 v[180:181], s[44:45], 0, v[160:161]
	global_load_lds_dwordx4 v162, s[52:53]
	s_add_i32 m0, s54, 0x2000
	s_nop 0
	global_load_lds_dwordx4 v158, s[52:53]
	s_mov_b32 m0, s14
	v_lshl_add_u64 v[176:177], s[44:45], 0, v[164:165]
	global_load_lds_dwordx4 v[176:177], off
	s_mov_b32 m0, s15
	s_nop 0
	global_load_lds_dwordx4 v[180:181], off
	s_waitcnt vmcnt(8) lgkmcnt(0)
	s_barrier
	v_mfma_f32_16x16x32_bf16 v[62:65], v[130:133], v[196:199], v[62:65]
	v_mfma_f32_16x16x32_bf16 v[58:61], v[138:141], v[196:199], v[58:61]
	v_mfma_f32_16x16x32_bf16 v[54:57], v[130:133], v[210:213], v[54:57]
	v_mfma_f32_16x16x32_bf16 v[46:49], v[138:141], v[210:213], v[46:49]
	v_mfma_f32_16x16x32_bf16 v[38:41], v[130:133], v[218:221], v[38:41]
	v_mfma_f32_16x16x32_bf16 v[30:33], v[138:141], v[218:221], v[30:33]
	v_mfma_f32_16x16x32_bf16 v[22:25], v[130:133], v[226:229], v[22:25]
	v_mfma_f32_16x16x32_bf16 v[14:17], v[138:141], v[226:229], v[14:17]
	v_mfma_f32_16x16x32_bf16 v[62:65], v[134:137], v[200:203], v[62:65]
	v_mfma_f32_16x16x32_bf16 v[58:61], v[142:145], v[200:203], v[58:61]
	v_mfma_f32_16x16x32_bf16 v[54:57], v[134:137], v[214:217], v[54:57]
	v_mfma_f32_16x16x32_bf16 v[46:49], v[142:145], v[214:217], v[46:49]
	v_mfma_f32_16x16x32_bf16 v[38:41], v[134:137], v[222:225], v[38:41]
	v_mfma_f32_16x16x32_bf16 v[30:33], v[142:145], v[222:225], v[30:33]
	v_mfma_f32_16x16x32_bf16 v[22:25], v[134:137], v[230:233], v[22:25]
	v_mfma_f32_16x16x32_bf16 v[14:17], v[142:145], v[230:233], v[14:17]
	v_mfma_f32_16x16x32_bf16 v[50:53], v[170:173], v[196:199], v[50:53]
	v_mfma_f32_16x16x32_bf16 v[42:45], v[188:191], v[196:199], v[42:45]
	v_mfma_f32_16x16x32_bf16 v[34:37], v[170:173], v[210:213], v[34:37]
	v_mfma_f32_16x16x32_bf16 v[26:29], v[188:191], v[210:213], v[26:29]
	v_mfma_f32_16x16x32_bf16 v[18:21], v[170:173], v[218:221], v[18:21]
	v_mfma_f32_16x16x32_bf16 v[10:13], v[188:191], v[218:221], v[10:13]
	v_mfma_f32_16x16x32_bf16 v[6:9], v[170:173], v[226:229], v[6:9]
	v_mfma_f32_16x16x32_bf16 v[2:5], v[188:191], v[226:229], v[2:5]
	v_mfma_f32_16x16x32_bf16 v[50:53], v[184:187], v[200:203], v[50:53]
	v_mfma_f32_16x16x32_bf16 v[42:45], v[192:195], v[200:203], v[42:45]
	v_mfma_f32_16x16x32_bf16 v[34:37], v[184:187], v[214:217], v[34:37]
	v_mfma_f32_16x16x32_bf16 v[26:29], v[192:195], v[214:217], v[26:29]
	v_mfma_f32_16x16x32_bf16 v[18:21], v[184:187], v[222:225], v[18:21]
	v_mfma_f32_16x16x32_bf16 v[10:13], v[192:195], v[222:225], v[10:13]
	v_mfma_f32_16x16x32_bf16 v[6:9], v[184:187], v[230:233], v[6:9]
	v_mfma_f32_16x16x32_bf16 v[2:5], v[192:195], v[230:233], v[2:5]
	s_barrier
	s_add_i32 s52, 0, 0x18000
	s_add_i32 s53, 0, 0x1c000
	ds_read_b128 v[130:133], v238
	ds_read_b128 v[134:137], v238 offset:1024
	ds_read_b128 v[138:141], v238 offset:2048
	ds_read_b128 v[142:145], v238 offset:3072
	ds_read_b128 v[170:173], v239
	ds_read_b128 v[184:187], v239 offset:1024
	ds_read_b128 v[188:191], v239 offset:2048
	ds_read_b128 v[192:195], v239 offset:3072
	s_add_u32 s44, s44, 0x80000
	s_addc_u32 s45, s45, 0
	s_mov_b32 m0, s16
	ds_read_b128 v[196:199], v183 offset:32768
	ds_read_b128 v[200:203], v183 offset:33792
	ds_read_b128 v[210:213], v183 offset:34816
	ds_read_b128 v[214:217], v183 offset:35840
	ds_read_b128 v[218:221], v183 offset:36864
	ds_read_b128 v[222:225], v183 offset:37888
	ds_read_b128 v[226:229], v183 offset:38912
	ds_read_b128 v[230:233], v183 offset:39936
	global_load_lds_dwordx4 v164, s[44:45]
	s_mov_b32 m0, s18
	s_nop 0
	global_load_lds_dwordx4 v160, s[44:45]
	s_waitcnt vmcnt(8) lgkmcnt(0)
	s_barrier
	v_mfma_f32_16x16x32_bf16 v[126:129], v[130:133], v[196:199], v[126:129]
	v_mfma_f32_16x16x32_bf16 v[122:125], v[138:141], v[196:199], v[122:125]
	v_mfma_f32_16x16x32_bf16 v[118:121], v[130:133], v[210:213], v[118:121]
	v_mfma_f32_16x16x32_bf16 v[110:113], v[138:141], v[210:213], v[110:113]
	v_mfma_f32_16x16x32_bf16 v[102:105], v[130:133], v[218:221], v[102:105]
	v_mfma_f32_16x16x32_bf16 v[94:97], v[138:141], v[218:221], v[94:97]
	v_mfma_f32_16x16x32_bf16 v[86:89], v[130:133], v[226:229], v[86:89]
	v_mfma_f32_16x16x32_bf16 v[78:81], v[138:141], v[226:229], v[78:81]
	v_mfma_f32_16x16x32_bf16 v[126:129], v[134:137], v[200:203], v[126:129]
	v_mfma_f32_16x16x32_bf16 v[122:125], v[142:145], v[200:203], v[122:125]
	v_mfma_f32_16x16x32_bf16 v[118:121], v[134:137], v[214:217], v[118:121]
	v_mfma_f32_16x16x32_bf16 v[110:113], v[142:145], v[214:217], v[110:113]
	v_mfma_f32_16x16x32_bf16 v[102:105], v[134:137], v[222:225], v[102:105]
	v_mfma_f32_16x16x32_bf16 v[94:97], v[142:145], v[222:225], v[94:97]
	v_mfma_f32_16x16x32_bf16 v[86:89], v[134:137], v[230:233], v[86:89]
	v_mfma_f32_16x16x32_bf16 v[78:81], v[142:145], v[230:233], v[78:81]
	v_mfma_f32_16x16x32_bf16 v[114:117], v[170:173], v[196:199], v[114:117]
	v_mfma_f32_16x16x32_bf16 v[106:109], v[188:191], v[196:199], v[106:109]
	v_mfma_f32_16x16x32_bf16 v[98:101], v[170:173], v[210:213], v[98:101]
	v_mfma_f32_16x16x32_bf16 v[90:93], v[188:191], v[210:213], v[90:93]
	v_mfma_f32_16x16x32_bf16 v[82:85], v[170:173], v[218:221], v[82:85]
	v_mfma_f32_16x16x32_bf16 v[74:77], v[188:191], v[218:221], v[74:77]
	v_mfma_f32_16x16x32_bf16 v[70:73], v[170:173], v[226:229], v[70:73]
	v_mfma_f32_16x16x32_bf16 v[66:69], v[188:191], v[226:229], v[66:69]
	v_mfma_f32_16x16x32_bf16 v[114:117], v[184:187], v[200:203], v[114:117]
	v_mfma_f32_16x16x32_bf16 v[106:109], v[192:195], v[200:203], v[106:109]
	v_mfma_f32_16x16x32_bf16 v[98:101], v[184:187], v[214:217], v[98:101]
	v_mfma_f32_16x16x32_bf16 v[90:93], v[192:195], v[214:217], v[90:93]
	v_mfma_f32_16x16x32_bf16 v[82:85], v[184:187], v[222:225], v[82:85]
	v_mfma_f32_16x16x32_bf16 v[74:77], v[192:195], v[222:225], v[74:77]
	v_mfma_f32_16x16x32_bf16 v[70:73], v[184:187], v[230:233], v[70:73]
	v_mfma_f32_16x16x32_bf16 v[66:69], v[192:195], v[230:233], v[66:69]
	s_barrier
	s_add_i32 s44, s52, s5
	s_mov_b32 m0, s44
	ds_read_b128 v[196:199], v183 offset:49152
	ds_read_b128 v[200:203], v183 offset:50176
	ds_read_b128 v[210:213], v183 offset:51200
	ds_read_b128 v[214:217], v183 offset:52224
	ds_read_b128 v[218:221], v183 offset:53248
	ds_read_b128 v[222:225], v183 offset:54272
	ds_read_b128 v[226:229], v183 offset:55296
	ds_read_b128 v[230:233], v183 offset:56320
	v_lshl_add_u64 v[154:155], v[154:155], 0, s[34:35]
	global_load_lds_dwordx4 v[154:155], off
	s_add_i32 m0, s44, 0x2000
	s_add_u32 s42, s42, 0x80080
	v_lshl_add_u64 v[154:155], v[156:157], 0, s[34:35]
	s_addc_u32 s43, s43, 0
	s_add_i32 s44, s53, s5
	global_load_lds_dwordx4 v[154:155], off
	s_mov_b32 m0, s44
	s_nop 0
	global_load_lds_dwordx4 v162, s[42:43]
	s_add_i32 m0, s44, 0x2000
	s_nop 0
	global_load_lds_dwordx4 v158, s[42:43]
	s_mov_b32 m0, s19
	v_lshl_add_u64 v[154:155], v[176:177], 0, s[34:35]
	global_load_lds_dwordx4 v[154:155], off
	s_mov_b32 m0, s25
	v_lshl_add_u64 v[154:155], v[180:181], 0, s[34:35]
	global_load_lds_dwordx4 v[154:155], off
	s_waitcnt vmcnt(8) lgkmcnt(0)
	s_barrier
	v_mfma_f32_16x16x32_bf16 v[62:65], v[130:133], v[196:199], v[62:65]
	v_mfma_f32_16x16x32_bf16 v[58:61], v[138:141], v[196:199], v[58:61]
	v_mfma_f32_16x16x32_bf16 v[54:57], v[130:133], v[210:213], v[54:57]
	v_mfma_f32_16x16x32_bf16 v[46:49], v[138:141], v[210:213], v[46:49]
	v_mfma_f32_16x16x32_bf16 v[38:41], v[130:133], v[218:221], v[38:41]
	v_mfma_f32_16x16x32_bf16 v[30:33], v[138:141], v[218:221], v[30:33]
	v_mfma_f32_16x16x32_bf16 v[22:25], v[130:133], v[226:229], v[22:25]
	v_mfma_f32_16x16x32_bf16 v[14:17], v[138:141], v[226:229], v[14:17]
	v_mfma_f32_16x16x32_bf16 v[62:65], v[134:137], v[200:203], v[62:65]
	v_mfma_f32_16x16x32_bf16 v[58:61], v[142:145], v[200:203], v[58:61]
	v_mfma_f32_16x16x32_bf16 v[54:57], v[134:137], v[214:217], v[54:57]
	v_mfma_f32_16x16x32_bf16 v[46:49], v[142:145], v[214:217], v[46:49]
	v_mfma_f32_16x16x32_bf16 v[38:41], v[134:137], v[222:225], v[38:41]
	v_mfma_f32_16x16x32_bf16 v[30:33], v[142:145], v[222:225], v[30:33]
	v_mfma_f32_16x16x32_bf16 v[22:25], v[134:137], v[230:233], v[22:25]
	v_mfma_f32_16x16x32_bf16 v[14:17], v[142:145], v[230:233], v[14:17]
	v_mfma_f32_16x16x32_bf16 v[50:53], v[170:173], v[196:199], v[50:53]
	v_mfma_f32_16x16x32_bf16 v[42:45], v[188:191], v[196:199], v[42:45]
	v_mfma_f32_16x16x32_bf16 v[34:37], v[170:173], v[210:213], v[34:37]
	v_mfma_f32_16x16x32_bf16 v[26:29], v[188:191], v[210:213], v[26:29]
	v_mfma_f32_16x16x32_bf16 v[18:21], v[170:173], v[218:221], v[18:21]
	v_mfma_f32_16x16x32_bf16 v[10:13], v[188:191], v[218:221], v[10:13]
	v_mfma_f32_16x16x32_bf16 v[6:9], v[170:173], v[226:229], v[6:9]
	v_mfma_f32_16x16x32_bf16 v[2:5], v[188:191], v[226:229], v[2:5]
	v_mfma_f32_16x16x32_bf16 v[50:53], v[184:187], v[200:203], v[50:53]
	v_mfma_f32_16x16x32_bf16 v[42:45], v[192:195], v[200:203], v[42:45]
	v_mfma_f32_16x16x32_bf16 v[34:37], v[184:187], v[214:217], v[34:37]
	v_mfma_f32_16x16x32_bf16 v[26:29], v[192:195], v[214:217], v[26:29]
	v_mfma_f32_16x16x32_bf16 v[18:21], v[184:187], v[222:225], v[18:21]
	v_mfma_f32_16x16x32_bf16 v[10:13], v[192:195], v[222:225], v[10:13]
	v_mfma_f32_16x16x32_bf16 v[6:9], v[184:187], v[230:233], v[6:9]
	v_mfma_f32_16x16x32_bf16 v[2:5], v[192:195], v[230:233], v[2:5]
	s_barrier
	s_add_i32 s51, s51, 2
	s_add_u32 s40, s40, 0x100
	s_addc_u32 s41, s41, 0
	s_add_u32 s49, s49, 0x100
	s_addc_u32 s50, s50, 0
	s_cmp_gt_u32 s51, 29
	s_cbranch_scc0 .LBB0_169
	s_setprio 0
	s_and_b64 vcc, exec, s[8:9]
	s_cbranch_vccz .LBB0_172
	s_barrier

.LBB0_516:
	s_add_u32 s46, s44, 0xfff80080
	s_addc_u32 s47, s45, -1
	s_add_i32 s58, 0, 0x10000
	s_cmp_eq_u32 s57, 28
	s_cselect_b32 s49, s21, s47
	s_cselect_b32 s48, s50, s46
	s_cselect_b32 s47, s13, s56
	s_cselect_b32 s46, s51, s55
	s_add_i32 s60, 0, 0x14000
	ds_read_b128 v[82:85], v236
	ds_read_b128 v[86:89], v236 offset:1024
	ds_read_b128 v[98:101], v236 offset:2048
	ds_read_b128 v[102:105], v236 offset:3072
	ds_read_b128 v[154:157], v237
	ds_read_b128 v[168:171], v237 offset:1024
	ds_read_b128 v[176:179], v237 offset:2048
	ds_read_b128 v[180:183], v237 offset:3072
	s_add_i32 m0, s14, 0xc000
	ds_read_b128 v[184:187], v174
	ds_read_b128 v[188:191], v174 offset:1024
	ds_read_b128 v[192:195], v174 offset:2048
	ds_read_b128 v[196:199], v174 offset:3072
	ds_read_b128 v[200:203], v174 offset:4096
	ds_read_b128 v[210:213], v174 offset:5120
	ds_read_b128 v[214:217], v174 offset:6144
	ds_read_b128 v[218:221], v174 offset:7168
	global_load_lds_dwordx4 v164, s[44:45]
	s_add_i32 m0, s14, 0xe000
	s_nop 0
	global_load_lds_dwordx4 v166, s[44:45]
	s_waitcnt vmcnt(8) lgkmcnt(0)
	s_barrier
	v_mfma_f32_16x16x32_bf16 v[142:145], v[82:85], v[184:187], v[142:145]
	v_mfma_f32_16x16x32_bf16 v[138:141], v[98:101], v[184:187], v[138:141]
	v_mfma_f32_16x16x32_bf16 v[126:129], v[82:85], v[192:195], v[126:129]
	v_mfma_f32_16x16x32_bf16 v[122:125], v[98:101], v[192:195], v[122:125]
	v_mfma_f32_16x16x32_bf16 v[110:113], v[82:85], v[200:203], v[110:113]
	v_mfma_f32_16x16x32_bf16 v[106:109], v[98:101], v[200:203], v[106:109]
	v_mfma_f32_16x16x32_bf16 v[78:81], v[82:85], v[214:217], v[78:81]
	v_mfma_f32_16x16x32_bf16 v[74:77], v[98:101], v[214:217], v[74:77]
	v_mfma_f32_16x16x32_bf16 v[142:145], v[86:89], v[188:191], v[142:145]
	v_mfma_f32_16x16x32_bf16 v[138:141], v[102:105], v[188:191], v[138:141]
	v_mfma_f32_16x16x32_bf16 v[126:129], v[86:89], v[196:199], v[126:129]
	v_mfma_f32_16x16x32_bf16 v[122:125], v[102:105], v[196:199], v[122:125]
	v_mfma_f32_16x16x32_bf16 v[110:113], v[86:89], v[210:213], v[110:113]
	v_mfma_f32_16x16x32_bf16 v[106:109], v[102:105], v[210:213], v[106:109]
	v_mfma_f32_16x16x32_bf16 v[78:81], v[86:89], v[218:221], v[78:81]
	v_mfma_f32_16x16x32_bf16 v[74:77], v[102:105], v[218:221], v[74:77]
	v_mfma_f32_16x16x32_bf16 v[134:137], v[154:157], v[184:187], v[134:137]
	v_mfma_f32_16x16x32_bf16 v[130:133], v[176:179], v[184:187], v[130:133]
	v_mfma_f32_16x16x32_bf16 v[118:121], v[154:157], v[192:195], v[118:121]
	v_mfma_f32_16x16x32_bf16 v[114:117], v[176:179], v[192:195], v[114:117]
	v_mfma_f32_16x16x32_bf16 v[94:97], v[154:157], v[200:203], v[94:97]
	v_mfma_f32_16x16x32_bf16 v[90:93], v[176:179], v[200:203], v[90:93]
	v_mfma_f32_16x16x32_bf16 v[70:73], v[154:157], v[214:217], v[70:73]
	v_mfma_f32_16x16x32_bf16 v[66:69], v[176:179], v[214:217], v[66:69]
	v_mfma_f32_16x16x32_bf16 v[134:137], v[168:171], v[188:191], v[134:137]
	v_mfma_f32_16x16x32_bf16 v[130:133], v[180:183], v[188:191], v[130:133]
	v_mfma_f32_16x16x32_bf16 v[118:121], v[168:171], v[196:199], v[118:121]
	v_mfma_f32_16x16x32_bf16 v[114:117], v[180:183], v[196:199], v[114:117]
	v_mfma_f32_16x16x32_bf16 v[94:97], v[168:171], v[210:213], v[94:97]
	v_mfma_f32_16x16x32_bf16 v[90:93], v[180:183], v[210:213], v[90:93]
	v_mfma_f32_16x16x32_bf16 v[70:73], v[168:171], v[218:221], v[70:73]
	v_mfma_f32_16x16x32_bf16 v[66:69], v[180:183], v[218:221], v[66:69]
	s_barrier
	s_add_i32 s58, s58, s5
	s_mov_b32 m0, s58
	ds_read_b128 v[184:187], v174 offset:16384
	ds_read_b128 v[188:191], v174 offset:17408
	ds_read_b128 v[192:195], v174 offset:18432
	ds_read_b128 v[196:199], v174 offset:19456
	ds_read_b128 v[200:203], v174 offset:20480
	ds_read_b128 v[210:213], v174 offset:21504
	ds_read_b128 v[214:217], v174 offset:22528
	ds_read_b128 v[218:221], v174 offset:23552
	v_lshl_add_u64 v[222:223], s[46:47], 0, v[0:1]
	global_load_lds_dwordx4 v[222:223], off
	s_add_i32 m0, s58, 0x2000
	s_add_u32 s58, s46, 0x80000
	v_lshl_add_u64 v[224:225], s[46:47], 0, v[158:159]
	s_addc_u32 s59, s47, 0
	s_add_i32 s60, s60, s5
	global_load_lds_dwordx4 v[224:225], off
	s_mov_b32 m0, s60
	v_lshl_add_u64 v[228:229], s[48:49], 0, v[160:161]
	global_load_lds_dwordx4 v0, s[58:59]
	s_add_i32 m0, s60, 0x2000
	s_nop 0
	global_load_lds_dwordx4 v158, s[58:59]
	s_mov_b32 m0, s14
	v_lshl_add_u64 v[226:227], s[48:49], 0, v[162:163]
	global_load_lds_dwordx4 v[226:227], off
	s_mov_b32 m0, s15
	s_nop 0
	global_load_lds_dwordx4 v[228:229], off
	s_waitcnt vmcnt(8) lgkmcnt(0)
	s_barrier
	v_mfma_f32_16x16x32_bf16 v[62:65], v[82:85], v[184:187], v[62:65]
	v_mfma_f32_16x16x32_bf16 v[58:61], v[98:101], v[184:187], v[58:61]
	v_mfma_f32_16x16x32_bf16 v[46:49], v[82:85], v[192:195], v[46:49]
	v_mfma_f32_16x16x32_bf16 v[42:45], v[98:101], v[192:195], v[42:45]
	v_mfma_f32_16x16x32_bf16 v[30:33], v[82:85], v[200:203], v[30:33]
	v_mfma_f32_16x16x32_bf16 v[26:29], v[98:101], v[200:203], v[26:29]
	v_mfma_f32_16x16x32_bf16 v[14:17], v[82:85], v[214:217], v[14:17]
	v_mfma_f32_16x16x32_bf16 v[10:13], v[98:101], v[214:217], v[10:13]
	v_mfma_f32_16x16x32_bf16 v[62:65], v[86:89], v[188:191], v[62:65]
	v_mfma_f32_16x16x32_bf16 v[58:61], v[102:105], v[188:191], v[58:61]
	v_mfma_f32_16x16x32_bf16 v[46:49], v[86:89], v[196:199], v[46:49]
	v_mfma_f32_16x16x32_bf16 v[42:45], v[102:105], v[196:199], v[42:45]
	v_mfma_f32_16x16x32_bf16 v[30:33], v[86:89], v[210:213], v[30:33]
	v_mfma_f32_16x16x32_bf16 v[26:29], v[102:105], v[210:213], v[26:29]
	v_mfma_f32_16x16x32_bf16 v[14:17], v[86:89], v[218:221], v[14:17]
	v_mfma_f32_16x16x32_bf16 v[10:13], v[102:105], v[218:221], v[10:13]
	v_mfma_f32_16x16x32_bf16 v[54:57], v[154:157], v[184:187], v[54:57]
	v_mfma_f32_16x16x32_bf16 v[50:53], v[176:179], v[184:187], v[50:53]
	v_mfma_f32_16x16x32_bf16 v[38:41], v[154:157], v[192:195], v[38:41]
	v_mfma_f32_16x16x32_bf16 v[34:37], v[176:179], v[192:195], v[34:37]
	v_mfma_f32_16x16x32_bf16 v[22:25], v[154:157], v[200:203], v[22:25]
	v_mfma_f32_16x16x32_bf16 v[18:21], v[176:179], v[200:203], v[18:21]
	v_mfma_f32_16x16x32_bf16 v[6:9], v[154:157], v[214:217], v[6:9]
	v_mfma_f32_16x16x32_bf16 v[2:5], v[176:179], v[214:217], v[2:5]
	v_mfma_f32_16x16x32_bf16 v[54:57], v[168:171], v[188:191], v[54:57]
	v_mfma_f32_16x16x32_bf16 v[50:53], v[180:183], v[188:191], v[50:53]
	v_mfma_f32_16x16x32_bf16 v[38:41], v[168:171], v[196:199], v[38:41]
	v_mfma_f32_16x16x32_bf16 v[34:37], v[180:183], v[196:199], v[34:37]
	v_mfma_f32_16x16x32_bf16 v[22:25], v[168:171], v[210:213], v[22:25]
	v_mfma_f32_16x16x32_bf16 v[18:21], v[180:183], v[210:213], v[18:21]
	v_mfma_f32_16x16x32_bf16 v[6:9], v[168:171], v[218:221], v[6:9]
	v_mfma_f32_16x16x32_bf16 v[2:5], v[180:183], v[218:221], v[2:5]
	s_barrier
	s_add_i32 s58, 0, 0x18000
	s_add_i32 s59, 0, 0x1c000
	ds_read_b128 v[82:85], v238
	ds_read_b128 v[86:89], v238 offset:1024
	ds_read_b128 v[98:101], v238 offset:2048
	ds_read_b128 v[102:105], v238 offset:3072
	ds_read_b128 v[154:157], v239
	ds_read_b128 v[168:171], v239 offset:1024
	ds_read_b128 v[176:179], v239 offset:2048
	ds_read_b128 v[180:183], v239 offset:3072
	s_add_u32 s48, s48, 0x80000
	s_addc_u32 s49, s49, 0
	s_mov_b32 m0, s16
	ds_read_b128 v[184:187], v174 offset:32768
	ds_read_b128 v[188:191], v174 offset:33792
	ds_read_b128 v[192:195], v174 offset:34816
	ds_read_b128 v[196:199], v174 offset:35840
	ds_read_b128 v[200:203], v174 offset:36864
	ds_read_b128 v[210:213], v174 offset:37888
	ds_read_b128 v[214:217], v174 offset:38912
	ds_read_b128 v[218:221], v174 offset:39936
	global_load_lds_dwordx4 v162, s[48:49]
	s_mov_b32 m0, s18
	s_nop 0
	global_load_lds_dwordx4 v160, s[48:49]
	s_waitcnt vmcnt(8) lgkmcnt(0)
	s_barrier
	v_mfma_f32_16x16x32_bf16 v[142:145], v[82:85], v[184:187], v[142:145]
	v_mfma_f32_16x16x32_bf16 v[138:141], v[98:101], v[184:187], v[138:141]
	v_mfma_f32_16x16x32_bf16 v[126:129], v[82:85], v[192:195], v[126:129]
	v_mfma_f32_16x16x32_bf16 v[122:125], v[98:101], v[192:195], v[122:125]
	v_mfma_f32_16x16x32_bf16 v[110:113], v[82:85], v[200:203], v[110:113]
	v_mfma_f32_16x16x32_bf16 v[106:109], v[98:101], v[200:203], v[106:109]
	v_mfma_f32_16x16x32_bf16 v[78:81], v[82:85], v[214:217], v[78:81]
	v_mfma_f32_16x16x32_bf16 v[74:77], v[98:101], v[214:217], v[74:77]
	v_mfma_f32_16x16x32_bf16 v[142:145], v[86:89], v[188:191], v[142:145]
	v_mfma_f32_16x16x32_bf16 v[138:141], v[102:105], v[188:191], v[138:141]
	v_mfma_f32_16x16x32_bf16 v[126:129], v[86:89], v[196:199], v[126:129]
	v_mfma_f32_16x16x32_bf16 v[122:125], v[102:105], v[196:199], v[122:125]
	v_mfma_f32_16x16x32_bf16 v[110:113], v[86:89], v[210:213], v[110:113]
	v_mfma_f32_16x16x32_bf16 v[106:109], v[102:105], v[210:213], v[106:109]
	v_mfma_f32_16x16x32_bf16 v[78:81], v[86:89], v[218:221], v[78:81]
	v_mfma_f32_16x16x32_bf16 v[74:77], v[102:105], v[218:221], v[74:77]
	v_mfma_f32_16x16x32_bf16 v[134:137], v[154:157], v[184:187], v[134:137]
	v_mfma_f32_16x16x32_bf16 v[130:133], v[176:179], v[184:187], v[130:133]
	v_mfma_f32_16x16x32_bf16 v[118:121], v[154:157], v[192:195], v[118:121]
	v_mfma_f32_16x16x32_bf16 v[114:117], v[176:179], v[192:195], v[114:117]
	v_mfma_f32_16x16x32_bf16 v[94:97], v[154:157], v[200:203], v[94:97]
	v_mfma_f32_16x16x32_bf16 v[90:93], v[176:179], v[200:203], v[90:93]
	v_mfma_f32_16x16x32_bf16 v[70:73], v[154:157], v[214:217], v[70:73]
	v_mfma_f32_16x16x32_bf16 v[66:69], v[176:179], v[214:217], v[66:69]
	v_mfma_f32_16x16x32_bf16 v[134:137], v[168:171], v[188:191], v[134:137]
	v_mfma_f32_16x16x32_bf16 v[130:133], v[180:183], v[188:191], v[130:133]
	v_mfma_f32_16x16x32_bf16 v[118:121], v[168:171], v[196:199], v[118:121]
	v_mfma_f32_16x16x32_bf16 v[114:117], v[180:183], v[196:199], v[114:117]
	v_mfma_f32_16x16x32_bf16 v[94:97], v[168:171], v[210:213], v[94:97]
	v_mfma_f32_16x16x32_bf16 v[90:93], v[180:183], v[210:213], v[90:93]
	v_mfma_f32_16x16x32_bf16 v[70:73], v[168:171], v[218:221], v[70:73]
	v_mfma_f32_16x16x32_bf16 v[66:69], v[180:183], v[218:221], v[66:69]
	s_barrier
	s_add_i32 s48, s58, s5
	s_mov_b32 m0, s48
	ds_read_b128 v[184:187], v174 offset:49152
	ds_read_b128 v[188:191], v174 offset:50176
	ds_read_b128 v[192:195], v174 offset:51200
	ds_read_b128 v[196:199], v174 offset:52224
	ds_read_b128 v[200:203], v174 offset:53248
	ds_read_b128 v[210:213], v174 offset:54272
	ds_read_b128 v[214:217], v174 offset:55296
	ds_read_b128 v[218:221], v174 offset:56320
	v_lshl_add_u64 v[222:223], v[222:223], 0, s[34:35]
	global_load_lds_dwordx4 v[222:223], off
	s_add_i32 m0, s48, 0x2000
	s_add_u32 s46, s46, 0x80080
	v_lshl_add_u64 v[222:223], v[224:225], 0, s[34:35]
	s_addc_u32 s47, s47, 0
	s_add_i32 s48, s59, s5
	global_load_lds_dwordx4 v[222:223], off
	s_mov_b32 m0, s48
	s_nop 0
	global_load_lds_dwordx4 v0, s[46:47]
	s_add_i32 m0, s48, 0x2000
	s_nop 0
	global_load_lds_dwordx4 v158, s[46:47]
	s_mov_b32 m0, s25
	v_lshl_add_u64 v[222:223], v[226:227], 0, s[34:35]
	global_load_lds_dwordx4 v[222:223], off
	s_mov_b32 m0, s33
	v_lshl_add_u64 v[222:223], v[228:229], 0, s[34:35]
	global_load_lds_dwordx4 v[222:223], off
	s_waitcnt vmcnt(8) lgkmcnt(0)
	s_barrier
	v_mfma_f32_16x16x32_bf16 v[62:65], v[82:85], v[184:187], v[62:65]
	v_mfma_f32_16x16x32_bf16 v[58:61], v[98:101], v[184:187], v[58:61]
	v_mfma_f32_16x16x32_bf16 v[46:49], v[82:85], v[192:195], v[46:49]
	v_mfma_f32_16x16x32_bf16 v[42:45], v[98:101], v[192:195], v[42:45]
	v_mfma_f32_16x16x32_bf16 v[30:33], v[82:85], v[200:203], v[30:33]
	v_mfma_f32_16x16x32_bf16 v[26:29], v[98:101], v[200:203], v[26:29]
	v_mfma_f32_16x16x32_bf16 v[14:17], v[82:85], v[214:217], v[14:17]
	v_mfma_f32_16x16x32_bf16 v[10:13], v[98:101], v[214:217], v[10:13]
	v_mfma_f32_16x16x32_bf16 v[62:65], v[86:89], v[188:191], v[62:65]
	v_mfma_f32_16x16x32_bf16 v[58:61], v[102:105], v[188:191], v[58:61]
	v_mfma_f32_16x16x32_bf16 v[46:49], v[86:89], v[196:199], v[46:49]
	v_mfma_f32_16x16x32_bf16 v[42:45], v[102:105], v[196:199], v[42:45]
	v_mfma_f32_16x16x32_bf16 v[30:33], v[86:89], v[210:213], v[30:33]
	v_mfma_f32_16x16x32_bf16 v[26:29], v[102:105], v[210:213], v[26:29]
	v_mfma_f32_16x16x32_bf16 v[14:17], v[86:89], v[218:221], v[14:17]
	v_mfma_f32_16x16x32_bf16 v[10:13], v[102:105], v[218:221], v[10:13]
	v_mfma_f32_16x16x32_bf16 v[54:57], v[154:157], v[184:187], v[54:57]
	v_mfma_f32_16x16x32_bf16 v[50:53], v[176:179], v[184:187], v[50:53]
	v_mfma_f32_16x16x32_bf16 v[38:41], v[154:157], v[192:195], v[38:41]
	v_mfma_f32_16x16x32_bf16 v[34:37], v[176:179], v[192:195], v[34:37]
	v_mfma_f32_16x16x32_bf16 v[22:25], v[154:157], v[200:203], v[22:25]
	v_mfma_f32_16x16x32_bf16 v[18:21], v[176:179], v[200:203], v[18:21]
	v_mfma_f32_16x16x32_bf16 v[6:9], v[154:157], v[214:217], v[6:9]
	v_mfma_f32_16x16x32_bf16 v[2:5], v[176:179], v[214:217], v[2:5]
	v_mfma_f32_16x16x32_bf16 v[54:57], v[168:171], v[188:191], v[54:57]
	v_mfma_f32_16x16x32_bf16 v[50:53], v[180:183], v[188:191], v[50:53]
	v_mfma_f32_16x16x32_bf16 v[38:41], v[168:171], v[196:199], v[38:41]
	v_mfma_f32_16x16x32_bf16 v[34:37], v[180:183], v[196:199], v[34:37]
	v_mfma_f32_16x16x32_bf16 v[22:25], v[168:171], v[210:213], v[22:25]
	v_mfma_f32_16x16x32_bf16 v[18:21], v[180:183], v[210:213], v[18:21]
	v_mfma_f32_16x16x32_bf16 v[6:9], v[168:171], v[218:221], v[6:9]
	v_mfma_f32_16x16x32_bf16 v[2:5], v[180:183], v[218:221], v[2:5]
	s_barrier
	s_add_i32 s57, s57, 2
	s_add_u32 s44, s44, 0x100
	s_addc_u32 s45, s45, 0
	s_add_u32 s55, s55, 0x100
	s_addc_u32 s56, s56, 0
	s_cmp_gt_u32 s57, 29
	s_cbranch_scc0 .LBB0_516
	s_setprio 0
	s_and_b64 vcc, exec, s[10:11]
	s_cbranch_vccz .LBB0_519
	s_barrier

.LBB0_604:
	s_add_u32 s22, s6, 0xfff80080
	s_addc_u32 s23, s7, -1
	s_add_i32 s54, 0, 0x10000
	s_cmp_eq_u32 s53, 28
	s_cselect_b32 s47, s18, s23
	s_cselect_b32 s46, s19, s22
	s_cselect_b32 s23, s21, s52
	s_cselect_b32 s22, s25, s41
	s_add_i32 s56, 0, 0x14000
	ds_read_b128 v[130:133], v236
	ds_read_b128 v[134:137], v236 offset:1024
	ds_read_b128 v[154:157], v236 offset:2048
	ds_read_b128 v[162:165], v236 offset:3072
	ds_read_b128 v[166:169], v237
	ds_read_b128 v[170:173], v237 offset:1024
	ds_read_b128 v[180:183], v237 offset:2048
	ds_read_b128 v[184:187], v237 offset:3072
	s_add_i32 m0, s16, 0xc000
	ds_read_b128 v[188:191], v179
	ds_read_b128 v[192:195], v179 offset:1024
	ds_read_b128 v[196:199], v179 offset:2048
	ds_read_b128 v[200:203], v179 offset:3072
	ds_read_b128 v[210:213], v179 offset:4096
	ds_read_b128 v[214:217], v179 offset:5120
	ds_read_b128 v[218:221], v179 offset:6144
	ds_read_b128 v[222:225], v179 offset:7168
	global_load_lds_dwordx4 v158, s[6:7]
	s_add_i32 m0, s16, 0xe000
	s_nop 0
	global_load_lds_dwordx4 v160, s[6:7]
	s_waitcnt vmcnt(8) lgkmcnt(0)
	s_barrier
	v_mfma_f32_16x16x32_bf16 v[126:129], v[130:133], v[188:191], v[126:129]
	v_mfma_f32_16x16x32_bf16 v[122:125], v[154:157], v[188:191], v[122:125]
	v_mfma_f32_16x16x32_bf16 v[110:113], v[130:133], v[196:199], v[110:113]
	v_mfma_f32_16x16x32_bf16 v[106:109], v[154:157], v[196:199], v[106:109]
	v_mfma_f32_16x16x32_bf16 v[94:97], v[130:133], v[210:213], v[94:97]
	v_mfma_f32_16x16x32_bf16 v[90:93], v[154:157], v[210:213], v[90:93]
	v_mfma_f32_16x16x32_bf16 v[78:81], v[130:133], v[218:221], v[78:81]
	v_mfma_f32_16x16x32_bf16 v[74:77], v[154:157], v[218:221], v[74:77]
	v_mfma_f32_16x16x32_bf16 v[126:129], v[134:137], v[192:195], v[126:129]
	v_mfma_f32_16x16x32_bf16 v[122:125], v[162:165], v[192:195], v[122:125]
	v_mfma_f32_16x16x32_bf16 v[110:113], v[134:137], v[200:203], v[110:113]
	v_mfma_f32_16x16x32_bf16 v[106:109], v[162:165], v[200:203], v[106:109]
	v_mfma_f32_16x16x32_bf16 v[94:97], v[134:137], v[214:217], v[94:97]
	v_mfma_f32_16x16x32_bf16 v[90:93], v[162:165], v[214:217], v[90:93]
	v_mfma_f32_16x16x32_bf16 v[78:81], v[134:137], v[222:225], v[78:81]
	v_mfma_f32_16x16x32_bf16 v[74:77], v[162:165], v[222:225], v[74:77]
	v_mfma_f32_16x16x32_bf16 v[118:121], v[166:169], v[188:191], v[118:121]
	v_mfma_f32_16x16x32_bf16 v[114:117], v[180:183], v[188:191], v[114:117]
	v_mfma_f32_16x16x32_bf16 v[102:105], v[166:169], v[196:199], v[102:105]
	v_mfma_f32_16x16x32_bf16 v[98:101], v[180:183], v[196:199], v[98:101]
	v_mfma_f32_16x16x32_bf16 v[86:89], v[166:169], v[210:213], v[86:89]
	v_mfma_f32_16x16x32_bf16 v[82:85], v[180:183], v[210:213], v[82:85]
	v_mfma_f32_16x16x32_bf16 v[70:73], v[166:169], v[218:221], v[70:73]
	v_mfma_f32_16x16x32_bf16 v[66:69], v[180:183], v[218:221], v[66:69]
	v_mfma_f32_16x16x32_bf16 v[118:121], v[170:173], v[192:195], v[118:121]
	v_mfma_f32_16x16x32_bf16 v[114:117], v[184:187], v[192:195], v[114:117]
	v_mfma_f32_16x16x32_bf16 v[102:105], v[170:173], v[200:203], v[102:105]
	v_mfma_f32_16x16x32_bf16 v[98:101], v[184:187], v[200:203], v[98:101]
	v_mfma_f32_16x16x32_bf16 v[86:89], v[170:173], v[214:217], v[86:89]
	v_mfma_f32_16x16x32_bf16 v[82:85], v[184:187], v[214:217], v[82:85]
	v_mfma_f32_16x16x32_bf16 v[70:73], v[170:173], v[222:225], v[70:73]
	v_mfma_f32_16x16x32_bf16 v[66:69], v[184:187], v[222:225], v[66:69]
	s_barrier
	s_add_i32 s54, s54, s15
	s_mov_b32 m0, s54
	ds_read_b128 v[188:191], v179 offset:16384
	ds_read_b128 v[192:195], v179 offset:17408
	ds_read_b128 v[196:199], v179 offset:18432
	ds_read_b128 v[200:203], v179 offset:19456
	ds_read_b128 v[210:213], v179 offset:20480
	ds_read_b128 v[214:217], v179 offset:21504
	ds_read_b128 v[218:221], v179 offset:22528
	ds_read_b128 v[222:225], v179 offset:23552
	v_lshl_add_u64 v[226:227], s[22:23], 0, v[142:143]
	global_load_lds_dwordx4 v[226:227], off
	s_add_i32 m0, s54, 0x2000
	s_add_u32 s54, s22, 0x80000
	v_lshl_add_u64 v[228:229], s[22:23], 0, v[138:139]
	s_addc_u32 s55, s23, 0
	s_add_i32 s56, s56, s15
	global_load_lds_dwordx4 v[228:229], off
	s_mov_b32 m0, s56
	v_lshl_add_u64 v[232:233], s[46:47], 0, v[140:141]
	global_load_lds_dwordx4 v142, s[54:55]
	s_add_i32 m0, s56, 0x2000
	s_nop 0
	global_load_lds_dwordx4 v138, s[54:55]
	s_mov_b32 m0, s16
	v_lshl_add_u64 v[230:231], s[46:47], 0, v[144:145]
	global_load_lds_dwordx4 v[230:231], off
	s_mov_b32 m0, s33
	s_nop 0
	global_load_lds_dwordx4 v[232:233], off
	s_waitcnt vmcnt(8) lgkmcnt(0)
	s_barrier
	v_mfma_f32_16x16x32_bf16 v[62:65], v[130:133], v[188:191], v[62:65]
	v_mfma_f32_16x16x32_bf16 v[58:61], v[154:157], v[188:191], v[58:61]
	v_mfma_f32_16x16x32_bf16 v[46:49], v[130:133], v[196:199], v[46:49]
	v_mfma_f32_16x16x32_bf16 v[42:45], v[154:157], v[196:199], v[42:45]
	v_mfma_f32_16x16x32_bf16 v[30:33], v[130:133], v[210:213], v[30:33]
	v_mfma_f32_16x16x32_bf16 v[26:29], v[154:157], v[210:213], v[26:29]
	v_mfma_f32_16x16x32_bf16 v[14:17], v[130:133], v[218:221], v[14:17]
	v_mfma_f32_16x16x32_bf16 v[10:13], v[154:157], v[218:221], v[10:13]
	v_mfma_f32_16x16x32_bf16 v[62:65], v[134:137], v[192:195], v[62:65]
	v_mfma_f32_16x16x32_bf16 v[58:61], v[162:165], v[192:195], v[58:61]
	v_mfma_f32_16x16x32_bf16 v[46:49], v[134:137], v[200:203], v[46:49]
	v_mfma_f32_16x16x32_bf16 v[42:45], v[162:165], v[200:203], v[42:45]
	v_mfma_f32_16x16x32_bf16 v[30:33], v[134:137], v[214:217], v[30:33]
	v_mfma_f32_16x16x32_bf16 v[26:29], v[162:165], v[214:217], v[26:29]
	v_mfma_f32_16x16x32_bf16 v[14:17], v[134:137], v[222:225], v[14:17]
	v_mfma_f32_16x16x32_bf16 v[10:13], v[162:165], v[222:225], v[10:13]
	v_mfma_f32_16x16x32_bf16 v[54:57], v[166:169], v[188:191], v[54:57]
	v_mfma_f32_16x16x32_bf16 v[50:53], v[180:183], v[188:191], v[50:53]
	v_mfma_f32_16x16x32_bf16 v[38:41], v[166:169], v[196:199], v[38:41]
	v_mfma_f32_16x16x32_bf16 v[34:37], v[180:183], v[196:199], v[34:37]
	v_mfma_f32_16x16x32_bf16 v[22:25], v[166:169], v[210:213], v[22:25]
	v_mfma_f32_16x16x32_bf16 v[18:21], v[180:183], v[210:213], v[18:21]
	v_mfma_f32_16x16x32_bf16 v[6:9], v[166:169], v[218:221], v[6:9]
	v_mfma_f32_16x16x32_bf16 v[2:5], v[180:183], v[218:221], v[2:5]
	v_mfma_f32_16x16x32_bf16 v[54:57], v[170:173], v[192:195], v[54:57]
	v_mfma_f32_16x16x32_bf16 v[50:53], v[184:187], v[192:195], v[50:53]
	v_mfma_f32_16x16x32_bf16 v[38:41], v[170:173], v[200:203], v[38:41]
	v_mfma_f32_16x16x32_bf16 v[34:37], v[184:187], v[200:203], v[34:37]
	v_mfma_f32_16x16x32_bf16 v[22:25], v[170:173], v[214:217], v[22:25]
	v_mfma_f32_16x16x32_bf16 v[18:21], v[184:187], v[214:217], v[18:21]
	v_mfma_f32_16x16x32_bf16 v[6:9], v[170:173], v[222:225], v[6:9]
	v_mfma_f32_16x16x32_bf16 v[2:5], v[184:187], v[222:225], v[2:5]
	s_barrier
	s_add_i32 s54, 0, 0x18000
	s_add_i32 s55, 0, 0x1c000
	ds_read_b128 v[130:133], v238
	ds_read_b128 v[134:137], v238 offset:1024
	ds_read_b128 v[154:157], v238 offset:2048
	ds_read_b128 v[162:165], v238 offset:3072
	ds_read_b128 v[166:169], v239
	ds_read_b128 v[170:173], v239 offset:1024
	ds_read_b128 v[180:183], v239 offset:2048
	ds_read_b128 v[184:187], v239 offset:3072
	s_add_u32 s46, s46, 0x80000
	s_addc_u32 s47, s47, 0
	s_mov_b32 m0, s37
	ds_read_b128 v[188:191], v179 offset:32768
	ds_read_b128 v[192:195], v179 offset:33792
	ds_read_b128 v[196:199], v179 offset:34816
	ds_read_b128 v[200:203], v179 offset:35840
	ds_read_b128 v[210:213], v179 offset:36864
	ds_read_b128 v[214:217], v179 offset:37888
	ds_read_b128 v[218:221], v179 offset:38912
	ds_read_b128 v[222:225], v179 offset:39936
	global_load_lds_dwordx4 v144, s[46:47]
	s_mov_b32 m0, s48
	s_nop 0
	global_load_lds_dwordx4 v140, s[46:47]
	s_waitcnt vmcnt(8) lgkmcnt(0)
	s_barrier
	v_mfma_f32_16x16x32_bf16 v[126:129], v[130:133], v[188:191], v[126:129]
	v_mfma_f32_16x16x32_bf16 v[122:125], v[154:157], v[188:191], v[122:125]
	v_mfma_f32_16x16x32_bf16 v[110:113], v[130:133], v[196:199], v[110:113]
	v_mfma_f32_16x16x32_bf16 v[106:109], v[154:157], v[196:199], v[106:109]
	v_mfma_f32_16x16x32_bf16 v[94:97], v[130:133], v[210:213], v[94:97]
	v_mfma_f32_16x16x32_bf16 v[90:93], v[154:157], v[210:213], v[90:93]
	v_mfma_f32_16x16x32_bf16 v[78:81], v[130:133], v[218:221], v[78:81]
	v_mfma_f32_16x16x32_bf16 v[74:77], v[154:157], v[218:221], v[74:77]
	v_mfma_f32_16x16x32_bf16 v[126:129], v[134:137], v[192:195], v[126:129]
	v_mfma_f32_16x16x32_bf16 v[122:125], v[162:165], v[192:195], v[122:125]
	v_mfma_f32_16x16x32_bf16 v[110:113], v[134:137], v[200:203], v[110:113]
	v_mfma_f32_16x16x32_bf16 v[106:109], v[162:165], v[200:203], v[106:109]
	v_mfma_f32_16x16x32_bf16 v[94:97], v[134:137], v[214:217], v[94:97]
	v_mfma_f32_16x16x32_bf16 v[90:93], v[162:165], v[214:217], v[90:93]
	v_mfma_f32_16x16x32_bf16 v[78:81], v[134:137], v[222:225], v[78:81]
	v_mfma_f32_16x16x32_bf16 v[74:77], v[162:165], v[222:225], v[74:77]
	v_mfma_f32_16x16x32_bf16 v[118:121], v[166:169], v[188:191], v[118:121]
	v_mfma_f32_16x16x32_bf16 v[114:117], v[180:183], v[188:191], v[114:117]
	v_mfma_f32_16x16x32_bf16 v[102:105], v[166:169], v[196:199], v[102:105]
	v_mfma_f32_16x16x32_bf16 v[98:101], v[180:183], v[196:199], v[98:101]
	v_mfma_f32_16x16x32_bf16 v[86:89], v[166:169], v[210:213], v[86:89]
	v_mfma_f32_16x16x32_bf16 v[82:85], v[180:183], v[210:213], v[82:85]
	v_mfma_f32_16x16x32_bf16 v[70:73], v[166:169], v[218:221], v[70:73]
	v_mfma_f32_16x16x32_bf16 v[66:69], v[180:183], v[218:221], v[66:69]
	v_mfma_f32_16x16x32_bf16 v[118:121], v[170:173], v[192:195], v[118:121]
	v_mfma_f32_16x16x32_bf16 v[114:117], v[184:187], v[192:195], v[114:117]
	v_mfma_f32_16x16x32_bf16 v[102:105], v[170:173], v[200:203], v[102:105]
	v_mfma_f32_16x16x32_bf16 v[98:101], v[184:187], v[200:203], v[98:101]
	v_mfma_f32_16x16x32_bf16 v[86:89], v[170:173], v[214:217], v[86:89]
	v_mfma_f32_16x16x32_bf16 v[82:85], v[184:187], v[214:217], v[82:85]
	v_mfma_f32_16x16x32_bf16 v[70:73], v[170:173], v[222:225], v[70:73]
	v_mfma_f32_16x16x32_bf16 v[66:69], v[184:187], v[222:225], v[66:69]
	s_barrier
	s_add_i32 s46, s54, s15
	s_mov_b32 m0, s46
	ds_read_b128 v[188:191], v179 offset:49152
	ds_read_b128 v[192:195], v179 offset:50176
	ds_read_b128 v[196:199], v179 offset:51200
	ds_read_b128 v[200:203], v179 offset:52224
	ds_read_b128 v[210:213], v179 offset:53248
	ds_read_b128 v[214:217], v179 offset:54272
	ds_read_b128 v[218:221], v179 offset:55296
	ds_read_b128 v[222:225], v179 offset:56320
	v_lshl_add_u64 v[226:227], v[226:227], 0, s[34:35]
	global_load_lds_dwordx4 v[226:227], off
	s_add_i32 m0, s46, 0x2000
	s_add_u32 s22, s22, 0x80080
	v_lshl_add_u64 v[226:227], v[228:229], 0, s[34:35]
	s_addc_u32 s23, s23, 0
	s_add_i32 s46, s55, s15
	global_load_lds_dwordx4 v[226:227], off
	s_mov_b32 m0, s46
	s_nop 0
	global_load_lds_dwordx4 v142, s[22:23]
	s_add_i32 m0, s46, 0x2000
	s_nop 0
	global_load_lds_dwordx4 v138, s[22:23]
	s_mov_b32 m0, s49
	v_lshl_add_u64 v[226:227], v[230:231], 0, s[34:35]
	global_load_lds_dwordx4 v[226:227], off
	s_mov_b32 m0, s50
	v_lshl_add_u64 v[226:227], v[232:233], 0, s[34:35]
	global_load_lds_dwordx4 v[226:227], off
	s_waitcnt vmcnt(8) lgkmcnt(0)
	s_barrier
	v_mfma_f32_16x16x32_bf16 v[62:65], v[130:133], v[188:191], v[62:65]
	v_mfma_f32_16x16x32_bf16 v[58:61], v[154:157], v[188:191], v[58:61]
	v_mfma_f32_16x16x32_bf16 v[46:49], v[130:133], v[196:199], v[46:49]
	v_mfma_f32_16x16x32_bf16 v[42:45], v[154:157], v[196:199], v[42:45]
	v_mfma_f32_16x16x32_bf16 v[30:33], v[130:133], v[210:213], v[30:33]
	v_mfma_f32_16x16x32_bf16 v[26:29], v[154:157], v[210:213], v[26:29]
	v_mfma_f32_16x16x32_bf16 v[14:17], v[130:133], v[218:221], v[14:17]
	v_mfma_f32_16x16x32_bf16 v[10:13], v[154:157], v[218:221], v[10:13]
	v_mfma_f32_16x16x32_bf16 v[62:65], v[134:137], v[192:195], v[62:65]
	v_mfma_f32_16x16x32_bf16 v[58:61], v[162:165], v[192:195], v[58:61]
	v_mfma_f32_16x16x32_bf16 v[46:49], v[134:137], v[200:203], v[46:49]
	v_mfma_f32_16x16x32_bf16 v[42:45], v[162:165], v[200:203], v[42:45]
	v_mfma_f32_16x16x32_bf16 v[30:33], v[134:137], v[214:217], v[30:33]
	v_mfma_f32_16x16x32_bf16 v[26:29], v[162:165], v[214:217], v[26:29]
	v_mfma_f32_16x16x32_bf16 v[14:17], v[134:137], v[222:225], v[14:17]
	v_mfma_f32_16x16x32_bf16 v[10:13], v[162:165], v[222:225], v[10:13]
	v_mfma_f32_16x16x32_bf16 v[54:57], v[166:169], v[188:191], v[54:57]
	v_mfma_f32_16x16x32_bf16 v[50:53], v[180:183], v[188:191], v[50:53]
	v_mfma_f32_16x16x32_bf16 v[38:41], v[166:169], v[196:199], v[38:41]
	v_mfma_f32_16x16x32_bf16 v[34:37], v[180:183], v[196:199], v[34:37]
	v_mfma_f32_16x16x32_bf16 v[22:25], v[166:169], v[210:213], v[22:25]
	v_mfma_f32_16x16x32_bf16 v[18:21], v[180:183], v[210:213], v[18:21]
	v_mfma_f32_16x16x32_bf16 v[6:9], v[166:169], v[218:221], v[6:9]
	v_mfma_f32_16x16x32_bf16 v[2:5], v[180:183], v[218:221], v[2:5]
	v_mfma_f32_16x16x32_bf16 v[54:57], v[170:173], v[192:195], v[54:57]
	v_mfma_f32_16x16x32_bf16 v[50:53], v[184:187], v[192:195], v[50:53]
	v_mfma_f32_16x16x32_bf16 v[38:41], v[170:173], v[200:203], v[38:41]
	v_mfma_f32_16x16x32_bf16 v[34:37], v[184:187], v[200:203], v[34:37]
	v_mfma_f32_16x16x32_bf16 v[22:25], v[170:173], v[214:217], v[22:25]
	v_mfma_f32_16x16x32_bf16 v[18:21], v[184:187], v[214:217], v[18:21]
	v_mfma_f32_16x16x32_bf16 v[6:9], v[170:173], v[222:225], v[6:9]
	v_mfma_f32_16x16x32_bf16 v[2:5], v[184:187], v[222:225], v[2:5]
	s_barrier
	s_add_i32 s53, s53, 2
	s_add_u32 s6, s6, 0x100
	s_addc_u32 s7, s7, 0
	s_add_u32 s41, s41, 0x100
	s_addc_u32 s52, s52, 0
	s_cmp_gt_u32 s53, 29
	s_cbranch_scc0 .LBB0_604
	s_setprio 0
	s_and_b64 vcc, exec, s[12:13]
	s_cbranch_vccz .LBB0_607
	s_barrier

.LBB0_728:
	s_add_u32 s42, s22, 0x100
	s_addc_u32 s43, s23, 0
	s_add_i32 s50, 0, 0x10000
	s_cmpk_eq_i32 s25, 0x54
	s_cselect_b32 s49, s21, s43
	s_cselect_b32 s48, s20, s42
	s_cselect_b32 s47, s45, s19
	s_cselect_b32 s46, s44, s18
	s_add_i32 s51, 0, 0x14000
	ds_read_b128 v[42:45], v236
	ds_read_b128 v[46:49], v236 offset:1024
	ds_read_b128 v[50:53], v236 offset:2048
	ds_read_b128 v[54:57], v236 offset:3072
	ds_read_b128 v[154:157], v237
	ds_read_b128 v[168:171], v237 offset:1024
	ds_read_b128 v[172:175], v237 offset:2048
	ds_read_b128 v[180:183], v237 offset:3072
	s_add_i32 m0, s33, 0xc000
	ds_read_b128 v[184:187], v178
	ds_read_b128 v[188:191], v178 offset:1024
	ds_read_b128 v[192:195], v178 offset:2048
	ds_read_b128 v[196:199], v178 offset:3072
	ds_read_b128 v[200:203], v178 offset:4096
	ds_read_b128 v[210:213], v178 offset:5120
	ds_read_b128 v[214:217], v178 offset:6144
	ds_read_b128 v[218:221], v178 offset:7168
	global_load_lds_dwordx4 v164, s[22:23]
	s_add_i32 m0, s33, 0xe000
	s_nop 0
	global_load_lds_dwordx4 v166, s[22:23]
	s_waitcnt vmcnt(8) lgkmcnt(0)
	s_barrier
	v_mfma_f32_16x16x32_bf16 v[142:145], v[42:45], v[184:187], v[142:145]
	v_mfma_f32_16x16x32_bf16 v[138:141], v[50:53], v[184:187], v[138:141]
	v_mfma_f32_16x16x32_bf16 v[126:129], v[42:45], v[192:195], v[126:129]
	v_mfma_f32_16x16x32_bf16 v[122:125], v[50:53], v[192:195], v[122:125]
	v_mfma_f32_16x16x32_bf16 v[110:113], v[42:45], v[200:203], v[110:113]
	v_mfma_f32_16x16x32_bf16 v[106:109], v[50:53], v[200:203], v[106:109]
	v_mfma_f32_16x16x32_bf16 v[94:97], v[42:45], v[214:217], v[94:97]
	v_mfma_f32_16x16x32_bf16 v[90:93], v[50:53], v[214:217], v[90:93]
	v_mfma_f32_16x16x32_bf16 v[142:145], v[46:49], v[188:191], v[142:145]
	v_mfma_f32_16x16x32_bf16 v[138:141], v[54:57], v[188:191], v[138:141]
	v_mfma_f32_16x16x32_bf16 v[126:129], v[46:49], v[196:199], v[126:129]
	v_mfma_f32_16x16x32_bf16 v[122:125], v[54:57], v[196:199], v[122:125]
	v_mfma_f32_16x16x32_bf16 v[110:113], v[46:49], v[210:213], v[110:113]
	v_mfma_f32_16x16x32_bf16 v[106:109], v[54:57], v[210:213], v[106:109]
	v_mfma_f32_16x16x32_bf16 v[94:97], v[46:49], v[218:221], v[94:97]
	v_mfma_f32_16x16x32_bf16 v[90:93], v[54:57], v[218:221], v[90:93]
	v_mfma_f32_16x16x32_bf16 v[134:137], v[154:157], v[184:187], v[134:137]
	v_mfma_f32_16x16x32_bf16 v[130:133], v[172:175], v[184:187], v[130:133]
	v_mfma_f32_16x16x32_bf16 v[118:121], v[154:157], v[192:195], v[118:121]
	v_mfma_f32_16x16x32_bf16 v[114:117], v[172:175], v[192:195], v[114:117]
	v_mfma_f32_16x16x32_bf16 v[102:105], v[154:157], v[200:203], v[102:105]
	v_mfma_f32_16x16x32_bf16 v[98:101], v[172:175], v[200:203], v[98:101]
	v_mfma_f32_16x16x32_bf16 v[86:89], v[154:157], v[214:217], v[86:89]
	v_mfma_f32_16x16x32_bf16 v[82:85], v[172:175], v[214:217], v[82:85]
	v_mfma_f32_16x16x32_bf16 v[134:137], v[168:171], v[188:191], v[134:137]
	v_mfma_f32_16x16x32_bf16 v[130:133], v[180:183], v[188:191], v[130:133]
	v_mfma_f32_16x16x32_bf16 v[118:121], v[168:171], v[196:199], v[118:121]
	v_mfma_f32_16x16x32_bf16 v[114:117], v[180:183], v[196:199], v[114:117]
	v_mfma_f32_16x16x32_bf16 v[102:105], v[168:171], v[210:213], v[102:105]
	v_mfma_f32_16x16x32_bf16 v[98:101], v[180:183], v[210:213], v[98:101]
	v_mfma_f32_16x16x32_bf16 v[86:89], v[168:171], v[218:221], v[86:89]
	v_mfma_f32_16x16x32_bf16 v[82:85], v[180:183], v[218:221], v[82:85]
	s_barrier
	s_add_i32 s22, s50, s16
	s_mov_b32 m0, s22
	ds_read_b128 v[184:187], v178 offset:16384
	ds_read_b128 v[188:191], v178 offset:17408
	ds_read_b128 v[192:195], v178 offset:18432
	ds_read_b128 v[196:199], v178 offset:19456
	ds_read_b128 v[200:203], v178 offset:20480
	ds_read_b128 v[210:213], v178 offset:21504
	ds_read_b128 v[214:217], v178 offset:22528
	ds_read_b128 v[218:221], v178 offset:23552
	v_lshl_add_u64 v[222:223], s[46:47], 0, v[0:1]
	global_load_lds_dwordx4 v[222:223], off
	s_add_i32 m0, s22, 0x2000
	s_add_u32 s22, s46, 0x160000
	v_lshl_add_u64 v[224:225], s[46:47], 0, v[158:159]
	s_addc_u32 s23, s47, 0
	s_add_i32 s50, s51, s16
	global_load_lds_dwordx4 v[224:225], off
	s_mov_b32 m0, s50
	v_lshl_add_u64 v[228:229], s[48:49], 0, v[160:161]
	global_load_lds_dwordx4 v0, s[22:23]
	s_add_i32 m0, s50, 0x2000
	s_nop 0
	global_load_lds_dwordx4 v158, s[22:23]
	s_mov_b32 m0, s33
	v_lshl_add_u64 v[226:227], s[48:49], 0, v[162:163]
	global_load_lds_dwordx4 v[226:227], off
	s_mov_b32 m0, s37
	s_nop 0
	global_load_lds_dwordx4 v[228:229], off
	s_waitcnt vmcnt(8) lgkmcnt(0)
	s_barrier
	v_mfma_f32_16x16x32_bf16 v[78:81], v[42:45], v[184:187], v[78:81]
	v_mfma_f32_16x16x32_bf16 v[74:77], v[50:53], v[184:187], v[74:77]
	v_mfma_f32_16x16x32_bf16 v[62:65], v[42:45], v[192:195], v[62:65]
	v_mfma_f32_16x16x32_bf16 v[58:61], v[50:53], v[192:195], v[58:61]
	v_mfma_f32_16x16x32_bf16 v[30:33], v[42:45], v[200:203], v[30:33]
	v_mfma_f32_16x16x32_bf16 v[26:29], v[50:53], v[200:203], v[26:29]
	v_mfma_f32_16x16x32_bf16 v[14:17], v[42:45], v[214:217], v[14:17]
	v_mfma_f32_16x16x32_bf16 v[10:13], v[50:53], v[214:217], v[10:13]
	v_mfma_f32_16x16x32_bf16 v[78:81], v[46:49], v[188:191], v[78:81]
	v_mfma_f32_16x16x32_bf16 v[74:77], v[54:57], v[188:191], v[74:77]
	v_mfma_f32_16x16x32_bf16 v[62:65], v[46:49], v[196:199], v[62:65]
	v_mfma_f32_16x16x32_bf16 v[58:61], v[54:57], v[196:199], v[58:61]
	v_mfma_f32_16x16x32_bf16 v[30:33], v[46:49], v[210:213], v[30:33]
	v_mfma_f32_16x16x32_bf16 v[26:29], v[54:57], v[210:213], v[26:29]
	v_mfma_f32_16x16x32_bf16 v[14:17], v[46:49], v[218:221], v[14:17]
	v_mfma_f32_16x16x32_bf16 v[10:13], v[54:57], v[218:221], v[10:13]
	v_mfma_f32_16x16x32_bf16 v[38:41], v[154:157], v[192:195], v[38:41]
	v_mfma_f32_16x16x32_bf16 v[34:37], v[172:175], v[192:195], v[34:37]
	v_mfma_f32_16x16x32_bf16 v[22:25], v[154:157], v[200:203], v[22:25]
	v_mfma_f32_16x16x32_bf16 v[18:21], v[172:175], v[200:203], v[18:21]
	v_mfma_f32_16x16x32_bf16 v[6:9], v[154:157], v[214:217], v[6:9]
	v_mfma_f32_16x16x32_bf16 v[2:5], v[172:175], v[214:217], v[2:5]
	v_mfma_f32_16x16x32_bf16 v[42:45], v[154:157], v[184:187], v[70:73]
	v_mfma_f32_16x16x32_bf16 v[46:49], v[172:175], v[184:187], v[66:69]
	v_mfma_f32_16x16x32_bf16 v[38:41], v[168:171], v[196:199], v[38:41]
	v_mfma_f32_16x16x32_bf16 v[34:37], v[180:183], v[196:199], v[34:37]
	v_mfma_f32_16x16x32_bf16 v[22:25], v[168:171], v[210:213], v[22:25]
	v_mfma_f32_16x16x32_bf16 v[18:21], v[180:183], v[210:213], v[18:21]
	v_mfma_f32_16x16x32_bf16 v[6:9], v[168:171], v[218:221], v[6:9]
	v_mfma_f32_16x16x32_bf16 v[2:5], v[180:183], v[218:221], v[2:5]
	v_mfma_f32_16x16x32_bf16 v[42:45], v[168:171], v[188:191], v[42:45]
	v_mfma_f32_16x16x32_bf16 v[46:49], v[180:183], v[188:191], v[46:49]
	s_barrier
	s_add_i32 s50, 0, 0x18000
	s_add_i32 s51, 0, 0x1c000
	ds_read_b128 v[50:53], v238
	ds_read_b128 v[54:57], v238 offset:1024
	ds_read_b128 v[66:69], v238 offset:2048
	ds_read_b128 v[70:73], v238 offset:3072
	ds_read_b128 v[154:157], v239
	ds_read_b128 v[168:171], v239 offset:1024
	ds_read_b128 v[172:175], v239 offset:2048
	ds_read_b128 v[180:183], v239 offset:3072
	s_add_u32 s22, s48, 0x160000
	s_addc_u32 s23, s49, 0
	s_mov_b32 m0, s52
	ds_read_b128 v[184:187], v178 offset:32768
	ds_read_b128 v[188:191], v178 offset:33792
	ds_read_b128 v[192:195], v178 offset:34816
	ds_read_b128 v[196:199], v178 offset:35840
	ds_read_b128 v[200:203], v178 offset:36864
	ds_read_b128 v[210:213], v178 offset:37888
	ds_read_b128 v[214:217], v178 offset:38912
	ds_read_b128 v[218:221], v178 offset:39936
	global_load_lds_dwordx4 v162, s[22:23]
	s_mov_b32 m0, s53
	s_nop 0
	global_load_lds_dwordx4 v160, s[22:23]
	s_waitcnt vmcnt(8) lgkmcnt(0)
	s_barrier
	v_mfma_f32_16x16x32_bf16 v[142:145], v[50:53], v[184:187], v[142:145]
	v_mfma_f32_16x16x32_bf16 v[138:141], v[66:69], v[184:187], v[138:141]
	v_mfma_f32_16x16x32_bf16 v[126:129], v[50:53], v[192:195], v[126:129]
	v_mfma_f32_16x16x32_bf16 v[122:125], v[66:69], v[192:195], v[122:125]
	v_mfma_f32_16x16x32_bf16 v[110:113], v[50:53], v[200:203], v[110:113]
	v_mfma_f32_16x16x32_bf16 v[106:109], v[66:69], v[200:203], v[106:109]
	v_mfma_f32_16x16x32_bf16 v[94:97], v[50:53], v[214:217], v[94:97]
	v_mfma_f32_16x16x32_bf16 v[90:93], v[66:69], v[214:217], v[90:93]
	v_mfma_f32_16x16x32_bf16 v[142:145], v[54:57], v[188:191], v[142:145]
	v_mfma_f32_16x16x32_bf16 v[138:141], v[70:73], v[188:191], v[138:141]
	v_mfma_f32_16x16x32_bf16 v[126:129], v[54:57], v[196:199], v[126:129]
	v_mfma_f32_16x16x32_bf16 v[122:125], v[70:73], v[196:199], v[122:125]
	v_mfma_f32_16x16x32_bf16 v[110:113], v[54:57], v[210:213], v[110:113]
	v_mfma_f32_16x16x32_bf16 v[106:109], v[70:73], v[210:213], v[106:109]
	v_mfma_f32_16x16x32_bf16 v[94:97], v[54:57], v[218:221], v[94:97]
	v_mfma_f32_16x16x32_bf16 v[90:93], v[70:73], v[218:221], v[90:93]
	v_mfma_f32_16x16x32_bf16 v[134:137], v[154:157], v[184:187], v[134:137]
	v_mfma_f32_16x16x32_bf16 v[130:133], v[172:175], v[184:187], v[130:133]
	v_mfma_f32_16x16x32_bf16 v[118:121], v[154:157], v[192:195], v[118:121]
	v_mfma_f32_16x16x32_bf16 v[114:117], v[172:175], v[192:195], v[114:117]
	v_mfma_f32_16x16x32_bf16 v[102:105], v[154:157], v[200:203], v[102:105]
	v_mfma_f32_16x16x32_bf16 v[98:101], v[172:175], v[200:203], v[98:101]
	v_mfma_f32_16x16x32_bf16 v[86:89], v[154:157], v[214:217], v[86:89]
	v_mfma_f32_16x16x32_bf16 v[82:85], v[172:175], v[214:217], v[82:85]
	v_mfma_f32_16x16x32_bf16 v[134:137], v[168:171], v[188:191], v[134:137]
	v_mfma_f32_16x16x32_bf16 v[130:133], v[180:183], v[188:191], v[130:133]
	v_mfma_f32_16x16x32_bf16 v[118:121], v[168:171], v[196:199], v[118:121]
	v_mfma_f32_16x16x32_bf16 v[114:117], v[180:183], v[196:199], v[114:117]
	v_mfma_f32_16x16x32_bf16 v[102:105], v[168:171], v[210:213], v[102:105]
	v_mfma_f32_16x16x32_bf16 v[98:101], v[180:183], v[210:213], v[98:101]
	v_mfma_f32_16x16x32_bf16 v[86:89], v[168:171], v[218:221], v[86:89]
	v_mfma_f32_16x16x32_bf16 v[82:85], v[180:183], v[218:221], v[82:85]
	s_barrier
	s_add_i32 s22, s50, s16
	s_mov_b32 m0, s22
	ds_read_b128 v[184:187], v178 offset:49152
	ds_read_b128 v[188:191], v178 offset:50176
	ds_read_b128 v[192:195], v178 offset:51200
	ds_read_b128 v[196:199], v178 offset:52224
	ds_read_b128 v[200:203], v178 offset:53248
	ds_read_b128 v[210:213], v178 offset:54272
	ds_read_b128 v[214:217], v178 offset:55296
	ds_read_b128 v[218:221], v178 offset:56320
	v_lshl_add_u64 v[222:223], v[222:223], 0, s[34:35]
	global_load_lds_dwordx4 v[222:223], off
	s_add_i32 m0, s22, 0x2000
	s_add_u32 s22, s46, 0x160080
	v_lshl_add_u64 v[222:223], v[224:225], 0, s[34:35]
	s_addc_u32 s23, s47, 0
	s_add_i32 s46, s51, s16
	global_load_lds_dwordx4 v[222:223], off
	s_mov_b32 m0, s46
	s_nop 0
	global_load_lds_dwordx4 v0, s[22:23]
	s_add_i32 m0, s46, 0x2000
	s_nop 0
	global_load_lds_dwordx4 v158, s[22:23]
	s_mov_b32 m0, s55
	v_lshl_add_u64 v[222:223], v[226:227], 0, s[34:35]
	global_load_lds_dwordx4 v[222:223], off
	s_mov_b32 m0, s56
	v_lshl_add_u64 v[222:223], v[228:229], 0, s[34:35]
	global_load_lds_dwordx4 v[222:223], off
	s_waitcnt vmcnt(8) lgkmcnt(0)
	s_barrier
	v_mfma_f32_16x16x32_bf16 v[78:81], v[50:53], v[184:187], v[78:81]
	v_mfma_f32_16x16x32_bf16 v[74:77], v[66:69], v[184:187], v[74:77]
	v_mfma_f32_16x16x32_bf16 v[62:65], v[50:53], v[192:195], v[62:65]
	v_mfma_f32_16x16x32_bf16 v[58:61], v[66:69], v[192:195], v[58:61]
	v_mfma_f32_16x16x32_bf16 v[30:33], v[50:53], v[200:203], v[30:33]
	v_mfma_f32_16x16x32_bf16 v[26:29], v[66:69], v[200:203], v[26:29]
	v_mfma_f32_16x16x32_bf16 v[14:17], v[50:53], v[214:217], v[14:17]
	v_mfma_f32_16x16x32_bf16 v[10:13], v[66:69], v[214:217], v[10:13]
	v_mfma_f32_16x16x32_bf16 v[78:81], v[54:57], v[188:191], v[78:81]
	v_mfma_f32_16x16x32_bf16 v[74:77], v[70:73], v[188:191], v[74:77]
	v_mfma_f32_16x16x32_bf16 v[62:65], v[54:57], v[196:199], v[62:65]
	v_mfma_f32_16x16x32_bf16 v[58:61], v[70:73], v[196:199], v[58:61]
	v_mfma_f32_16x16x32_bf16 v[30:33], v[54:57], v[210:213], v[30:33]
	v_mfma_f32_16x16x32_bf16 v[26:29], v[70:73], v[210:213], v[26:29]
	v_mfma_f32_16x16x32_bf16 v[14:17], v[54:57], v[218:221], v[14:17]
	v_mfma_f32_16x16x32_bf16 v[10:13], v[70:73], v[218:221], v[10:13]
	v_mfma_f32_16x16x32_bf16 v[42:45], v[154:157], v[184:187], v[42:45]
	v_mfma_f32_16x16x32_bf16 v[70:73], v[168:171], v[188:191], v[42:45]
	v_mfma_f32_16x16x32_bf16 v[42:45], v[172:175], v[184:187], v[46:49]
	v_mfma_f32_16x16x32_bf16 v[38:41], v[154:157], v[192:195], v[38:41]
	v_mfma_f32_16x16x32_bf16 v[34:37], v[172:175], v[192:195], v[34:37]
	v_mfma_f32_16x16x32_bf16 v[22:25], v[154:157], v[200:203], v[22:25]
	v_mfma_f32_16x16x32_bf16 v[18:21], v[172:175], v[200:203], v[18:21]
	v_mfma_f32_16x16x32_bf16 v[6:9], v[154:157], v[214:217], v[6:9]
	v_mfma_f32_16x16x32_bf16 v[2:5], v[172:175], v[214:217], v[2:5]
	v_mfma_f32_16x16x32_bf16 v[66:69], v[180:183], v[188:191], v[42:45]
	v_mfma_f32_16x16x32_bf16 v[38:41], v[168:171], v[196:199], v[38:41]
	v_mfma_f32_16x16x32_bf16 v[34:37], v[180:183], v[196:199], v[34:37]
	v_mfma_f32_16x16x32_bf16 v[22:25], v[168:171], v[210:213], v[22:25]
	v_mfma_f32_16x16x32_bf16 v[18:21], v[180:183], v[210:213], v[18:21]
	v_mfma_f32_16x16x32_bf16 v[6:9], v[168:171], v[218:221], v[6:9]
	v_mfma_f32_16x16x32_bf16 v[2:5], v[180:183], v[218:221], v[2:5]
	s_barrier
	s_add_i32 s25, s25, 2
	s_add_u32 s18, s18, 0x100
	s_addc_u32 s19, s19, 0
	s_cmpk_gt_u32 s25, 0x55
	s_mov_b64 s[22:23], s[42:43]
	s_cbranch_scc0 .LBB0_728
	s_setprio 0
	s_and_b64 vcc, exec, s[12:13]
	s_cbranch_vccz .LBB0_731
	s_barrier
